# v22: v18 plus one static s_setprio 1 for waves 4-7 through the diff-attention phase
# baseline (speedup 1.0000x reference)
; #define LAS __attribute__((address_space(3)))
; #define LAUNDER_L LAUNDER_T int l = l_; asm volatile("" : "+s"(l)); const KParams p = kparams(); unsigned char* ws = p->ws; float* outp = p->out; (void)outp;
; DI void diff_attn_unit(int b, int h, int qb, const bf16_t* Z, const bf16_t* VT, bf16_t* H, float lam, const float* subg, float oscale, LAS unsigned char* lds, int wid, int lane) {
;     const int r32 = lane & 31, hi = lane >> 5, mp = wid >> 2, wq = wid & 3;
;     const int qrow = b * SEQ + qb * 128 + wq * 32 + r32;
;     bf16x8 qf[4];
; #pragma unroll
;     for (int ks = 0; ks < 4; ++ks) qf[ks] = *(const bf16x8*)(Z + (size_t)qrow * INC + h * 128 + mp * 64 + ks * 16 + hi * 8);
;     const int ntile = 2 * qb + 2, mylast = 2 * qb + (wq >> 1);
;     const bf16_t* kg[2]; const bf16_t* vg[2];
; #pragma unroll
;     for (int i = 0; i < 2; ++i) { const int q = i * 8 + wid;
;         { const int row = 4 * q + (lane >> 4), c = (lane & 15) ^ (row & 15); kg[i] = Z + (size_t)(b * SEQ + row) * INC + 512 + h * 128 + c * 8; }
;         { const int row = 8 * q + (lane >> 3), c = (lane & 7) ^ (row & 7); vg[i] = VT + (size_t)((b * 4 + h) * 128 + row) * SEQ + c * 8; } }
; __global__ void __launch_bounds__(NTHR, 2) fwd_megakernel(Params p_unused) {
;     ...
;         { LAUNDER_L
;             const bf16_t* Z = (const bf16_t*)(ws + WS_Z); bf16_t* H = (bf16_t*)(ws + WS_H); const bf16_t* VT = (const bf16_t*)(ws + WS_VT);
;             const float lam_init = lam_init_of(l);
;             float lam;
;             { const float a = wave_sum(p->in[12][l * 64 + lane] * p->in[13][l * 64 + lane]), b = wave_sum(p->in[14][l * 64 + lane] * p->in[15][l * 64 + lane]);
;               lam = __builtin_bit_cast(float, __builtin_amdgcn_readfirstlane(__builtin_bit_cast(int, expf(a) - expf(b) + lam_init))); }
;             const float* subg = p->in[16] + l * 128; const float oscale = 1.0f - lam_init;
;             const int vcu = (G % 8 == 0) ? (bx_ % 8) * (G / 8) + bx_ / 8 : bx_;
;             for (int pr = vcu; pr < NBATCH * 4 * 8; pr += G) { const int bh = pr >> 3, s = pr & 7;
;                 diff_attn_unit(bh >> 2, bh & 3, s, Z, VT, H, lam, subg, oscale, lds, wid, lane);
;                 diff_attn_unit(bh >> 2, bh & 3, 15 - s, Z, VT, H, lam, subg, oscale, lds, wid, lane); }
.LBB0_2214:
	s_lshl_b32 s2, s14, 7
	s_ashr_i32 s3, s2, 31
	s_lshl_b64 s[2:3], s[2:3], 2
	s_waitcnt lgkmcnt(0)
	s_add_u32 s42, s0, s2
	s_addc_u32 s43, s1, s3
	s_add_u32 s38, s46, 0x13a00000
	s_addc_u32 s39, s47, 0
	s_add_u32 s48, s46, 0x27c00000
	s_addc_u32 s49, s47, 0
	s_cmpk_gt_i32 s24, 0x3ff
	v_sub_f32_e32 v174, 1.0, v0
	s_cbranch_scc1 .LBB0_2237
	v_lshrrev_b32_e32 v176, 3, v117
	v_xor_b32_e32 v2, v176, v117
	v_lshlrev_b32_e32 v2, 4, v2
	v_and_b32_e32 v96, 0x70, v2
	v_lshl_add_u64 v[2:3], s[46:47], 0, v[96:97]
	s_mov_b64 s[2:3], 0x2fd00000
	v_lshrrev_b32_e32 v4, 4, v117
	v_lshl_add_u64 v[114:115], v[2:3], 0, s[2:3]
	s_add_i32 s2, s15, 8
	v_lshl_add_u32 v178, s2, 2, v4
	s_ashr_i32 s4, s15, 2
	v_xor_b32_e32 v3, v178, v117
	s_lshl_b32 s31, s2, 3
	s_lshl_b32 s2, s15, 10
	v_and_b32_e32 v175, 31, v117
	v_lshrrev_b32_e32 v1, 5, v117
	v_lshlrev_b32_e32 v3, 3, v3
	s_add_i32 s33, s2, 0
	s_lshl_b32 s2, s4, 3
	v_and_b32_e32 v6, 15, v117
	v_lshl_add_u32 v177, s15, 2, v4
	v_and_b32_e32 v4, 0x78, v3
	v_or_b32_e32 v3, s2, v1
	v_lshlrev_b32_e32 v5, 8, v175
	v_bitop3_b32 v8, v1, v6, s2 bitop3:0x36
	v_lshl_add_u32 v180, v8, 4, v5
	v_add_u32_e32 v8, 2, v3
	v_bitop3_b32 v6, v3, v6, 4 bitop3:0x36
	v_add_u32_e32 v3, 6, v3
	v_bitop3_b32 v3, v3, v117, 15 bitop3:0x78
	v_lshl_add_u32 v183, v3, 4, v5
	v_bitop3_b32 v3, v1, v117, 7 bitop3:0x78
	v_lshlrev_b32_e32 v184, 4, v3
	v_add_u32_e32 v3, 2, v1
	v_and_b32_e32 v7, 7, v117
	v_bitop3_b32 v3, v3, v117, 7 bitop3:0x78
	s_and_b32 s5, s15, 3
	v_lshlrev_b32_e32 v185, 4, v3
	v_bitop3_b32 v3, v1, v7, 4 bitop3:0x36
	s_lshl_b32 s8, s4, 6
	v_lshlrev_b32_e32 v186, 4, v3
	v_add_u32_e32 v3, 6, v1
	s_lshl_b32 s2, s5, 14
	s_lshl_b32 s0, s5, 5
	s_ashr_i32 s9, s8, 31
	s_bfe_u32 s1, s15, 0x10001
	s_lshl_b32 s25, s15, 3
	v_bitop3_b32 v3, v3, v117, 7 bitop3:0x78
	s_add_i32 s2, s2, 0
	v_lshlrev_b32_e32 v0, 3, v1
	v_xor_b32_e32 v2, v177, v117
	v_lshlrev_b32_e32 v187, 4, v3
	s_cmp_eq_u32 s4, 1
	v_lshlrev_b32_e32 v116, 2, v1
	v_lshlrev_b32_e32 v96, 4, v1
	v_bitop3_b32 v1, v176, 7, v117 bitop3:0x48
	v_mov_b32_e32 v3, 0x2fd00080
	v_lshlrev_b32_e32 v2, 3, v2
	s_cselect_b64 s[10:11], -1, 0
	s_cmp_lt_u32 s15, 4
	v_lshl_or_b32 v120, v1, 4, v3
	v_bitop3_b32 v1, v178, 15, v117 bitop3:0x48
	v_and_b32_e32 v2, 0x78, v2
	v_bitop3_b32 v8, v8, v117, 15 bitop3:0x78
	s_cselect_b64 s[40:41], -1, 0
	s_cmp_lt_u32 s15, 4
	s_cbranch_scc1 .Lda_prio_skip
	s_setprio 1
.Lda_prio_skip:
	s_cmp_gt_u32 s5, 1
	v_add_u32_e32 v189, s25, v176
	v_lshl_or_b32 v122, v1, 4, v228
	v_bitop3_b32 v1, v177, 15, v117 bitop3:0x48
	v_lshlrev_b32_e32 v179, 7, v175
	v_lshl_add_u32 v181, v8, 4, v5
	v_lshl_add_u32 v182, v6, 4, v5
	v_lshl_add_u32 v188, v117, 2, s2
	v_lshl_add_u64 v[118:119], s[42:43], 0, v[96:97]
	s_cselect_b64 s[50:51], -1, 0
	v_mov_b32_e32 v121, v97
	s_lshl_b32 s34, s24, 4
	v_add_u32_e32 v190, 64, v189
	v_mov_b32_e32 v123, v97
	v_lshl_or_b32 v124, v1, 4, v228
	v_mov_b32_e32 v125, v97
	v_lshlrev_b32_e32 v96, 1, v0
	v_lshlrev_b32_e32 v126, 1, v2
	v_lshlrev_b32_e32 v128, 1, v4
	s_mov_b32 s35, s24
	s_branch .LBB0_2217

; DI unsigned xb_add(unsigned* p, unsigned v) { return __hip_atomic_fetch_add(p, v, __ATOMIC_RELAXED, __HIP_MEMORY_SCOPE_AGENT); }
; DI bool xb_tid0(int wid) { unsigned m_ = ~0u; int w_ = wid; asm volatile("" : "+s"(m_), "+s"(w_)); return w_ == 0 && __builtin_amdgcn_mbcnt_hi(m_, __builtin_amdgcn_mbcnt_lo(m_, 0u)) == 0u; }
; DI void xcd_barrier(const XcdBarrier& b, int wid) {
;     asm volatile("s_waitcnt vmcnt(0)" ::: "memory");
;     __syncthreads();
;     if (xb_tid0(wid)) {
;         unsigned* bar = b.bar;
;         __builtin_amdgcn_s_waitcnt(0);
;         unsigned nloc = b.st[0], nx = b.st[1];
;         if (nloc == 0u) { xcd_barrier_complete(bar, b.x, nloc, nx); b.st[0] = nloc; b.st[1] = nx; }
;         const unsigned old = xb_add(&bar[XB_XSUB(b.x)], 1u);
.LBB0_2260:
	s_setprio 0
	s_waitcnt vmcnt(0)
	v_readlane_b32 s2, v255, 36
	s_mov_b32 s1, s2
	s_mov_b32 s0, -1
	v_readlane_b32 s10, v255, 43
	s_barrier
	s_cmp_lg_u32 s1, 0
	v_readlane_b32 s11, v255, 44
	s_cbranch_scc1 .LBB0_2314
	v_mbcnt_lo_u32_b32 v0, s0, 0
	v_mbcnt_hi_u32_b32 v0, s0, v0
	v_cmp_eq_u32_e32 vcc, 0, v0
	s_and_saveexec_b64 s[0:1], vcc
	s_cbranch_execz .LBB0_2313
	v_readlane_b32 s2, v255, 29
	s_waitcnt vmcnt(0) expcnt(0) lgkmcnt(0)
	s_nop 0
	v_mov_b32_e32 v0, s2
	ds_read_b32 v2, v0
	v_readlane_b32 s2, v255, 30
	s_waitcnt lgkmcnt(0)
	v_cmp_ne_u32_e32 vcc, 0, v2
	v_mov_b32_e32 v0, s2
	ds_read_b32 v0, v0
	s_cbranch_vccnz .LBB0_2277
	s_mov_b32 s6, 1
	s_branch .LBB0_2265
